# in_o tile prologue: ssx row-scale reduction moved behind the A/W load issue (loads into spare registers, one vmcnt(16))
# baseline (speedup 1.0000x reference)
; DI void ph_in_o(const Params& P, int g, bf16_t* smem, float* s_rs) {
;     ...
;   for (int it = 0;; it++) {
;     int mt, nt; if (!tile_sched256(bid, it, 20, 10, mt, nt)) break;
;     const int m0 = mt * 256, n0 = nt * 128;
;     __syncthreads();
;     {
;       const float4* pp = (const float4*)(ssx + (size_t)(m0 + tid) * 16);
;       float4 a = pp[0], b = pp[1], c = pp[2], d = pp[3];
;       float s = a.x + a.y + a.z + a.w + b.x + b.y + b.z + b.w + c.x + c.y + c.z + c.w + d.x + d.y + d.z + d.w;
;       s_rs[tid] = rsqrtf(s * (1.f / 1024.f) + EPS);
;     }
.LBB0_181:
	s_lshl_b32 s86, s29, 8
	v_add_u32_e32 v2, s86, v169
	v_ashrrev_i32_e32 v3, 31, v2
	v_readlane_b32 s2, v253, 45
	v_lshlrev_b64 v[2:3], 6, v[2:3]
	v_readlane_b32 s3, v253, 46
	s_barrier
	s_nop 0
	v_lshl_add_u64 v[14:15], s[2:3], 0, v[2:3]
	global_load_dwordx4 v[220:223], v[14:15], off offset:48
	global_load_dwordx4 v[224:227], v[14:15], off offset:32
	global_load_dwordx4 v[228:231], v[14:15], off offset:16
	s_nop 0
	global_load_dwordx4 v[212:215], v[14:15], off
	s_mov_b32 s2, 0x800000
	s_lshl_b32 s12, s6, 7
	v_readlane_b32 s8, v253, 47
	v_readlane_b32 s9, v253, 48


; #define ZERO_ACC8(a) { _Pragma("unroll") for (int i_ = 0; i_ < 8; i_++) _Pragma("unroll") for (int r_ = 0; r_ < 16; r_++) a[i_][r_] = 0.f; }
; DI void ph_in_o(const Params& P, int g, bf16_t* smem, float* s_rs) {
;     ...
;   for (int it = 0;; it++) {
;     int mt, nt; if (!tile_sched256(bid, it, 20, 10, mt, nt)) break;
;     const int m0 = mt * 256, n0 = nt * 128;
;     __syncthreads();
;     {
;       const float4* pp = (const float4*)(ssx + (size_t)(m0 + tid) * 16);
;       float4 a = pp[0], b = pp[1], c = pp[2], d = pp[3];
;       float s = a.x + a.y + a.z + a.w + b.x + b.y + b.z + b.w + c.x + c.y + c.z + c.w + d.x + d.y + d.z + d.w;
;       s_rs[tid] = rsqrtf(s * (1.f / 1024.f) + EPS);
;     }
;     f32x16 acc[8]; ZERO_ACC8(acc)
;     LoadTile256 la{x2b + (size_t)(2 * mt) * 16 * 8192, 16 * 8192};
;     const bool isY = (nt >= 8 && nt < 16);
;     gemm256(la, W + (size_t)n0 * 1024, 64, 16, smem, acc, !isY);
	s_lshl_b32 s2, s29, 1
	s_ashr_i32 s3, s2, 31
	s_lshl_b64 s[14:15], s[2:3], 18

; DI void ph_in_o(const Params& P, int g, bf16_t* smem, float* s_rs) {
;     ...
;     LoadTile256 la{x2b + (size_t)(2 * mt) * 16 * 8192, 16 * 8192};
	s_add_u32 s10, s82, s14

; DI void ph_in_o(const Params& P, int g, bf16_t* smem, float* s_rs) {
;     ...
;     LoadTile256 la{x2b + (size_t)(2 * mt) * 16 * 8192, 16 * 8192};
;     const bool isY = (nt >= 8 && nt < 16);
	s_addc_u32 s11, s83, s15
	s_and_b32 s18, s6, -8

; DI void ph_in_o(const Params& P, int g, bf16_t* smem, float* s_rs) {
;     ...
;     const bool isY = (nt >= 8 && nt < 16);
;     gemm256(la, W + (size_t)n0 * 1024, 64, 16, smem, acc, !isY);
	s_cmp_lg_u32 s18, 8
	s_cselect_b64 s[2:3], -1, 0
	s_ashr_i32 s13, s12, 31
	s_lshl_b64 s[16:17], s[12:13], 11
	s_add_u32 s8, s8, s16

; DI void ph_in_o(const Params& P, int g, bf16_t* smem, float* s_rs) {
;     ...
;     gemm256(la, W + (size_t)n0 * 1024, 64, 16, smem, acc, !isY);
	s_addc_u32 s9, s9, s17


; DI void ph_in_o(const Params& P, int g, bf16_t* smem, float* s_rs) {
;     ...
;     const bool isY = (nt >= 8 && nt < 16);
;     gemm256(la, W + (size_t)n0 * 1024, 64, 16, smem, acc, !isY);
	s_cmp_eq_u32 s18, 8
	s_mov_b64 s[18:19], -1

; #define A256_LOADH(kt_, hf_) { a0 = la.ld1(kt_, (hf_) * 4 + 0, tid); a1 = la.ld1(kt_, (hf_) * 4 + 1, tid); a2 = la.ld1(kt_, (hf_) * 4 + 2, tid); a3 = la.ld1(kt_, (hf_) * 4 + 3, tid); }
; #define ZERO_ACC8(a) { _Pragma("unroll") for (int i_ = 0; i_ < 8; i_++) _Pragma("unroll") for (int r_ = 0; r_ < 16; r_++) a[i_][r_] = 0.f; }
; template <bool swap, class LA>
; DI void gemm256_ws(const LA& la, const bf16_t* Wt, const int KS, const int nk, bf16_t* smem, f32x16 (&acc)[8]) {
;     ...
;   A256_LOADH(0, 0) A256_STH(smem, 0)
;   A256_LOADH(0, 1) A256_STH(smem, 1)
;   W256_LD(0, 0, w00, w10) W256_LD(0, 1, w01, w11) W256_LD(0, 2, w02, w12) W256_LD(0, 3, w03, w13)
;   __syncthreads();
;   const int aoff = (tbk * 128 + l32) * LDT + h * 8;
; DI void ph_in_o(const Params& P, int g, bf16_t* smem, float* s_rs) {
;     ...
;     {
;       const float4* pp = (const float4*)(ssx + (size_t)(m0 + tid) * 16);
;       float4 a = pp[0], b = pp[1], c = pp[2], d = pp[3];
;       float s = a.x + a.y + a.z + a.w + b.x + b.y + b.z + b.w + c.x + c.y + c.z + c.w + d.x + d.y + d.z + d.w;
;       s_rs[tid] = rsqrtf(s * (1.f / 1024.f) + EPS);
;     }
;     f32x16 acc[8]; ZERO_ACC8(acc)
;     LoadTile256 la{x2b + (size_t)(2 * mt) * 16 * 8192, 16 * 8192};
;     const bool isY = (nt >= 8 && nt < 16);
;     gemm256(la, W + (size_t)n0 * 1024, 64, 16, smem, acc, !isY);
	s_cbranch_scc1 .LBB0_194
	v_mov_b32_e32 v0, v234
	s_add_u32 s18, s10, 0x40000
	v_lshlrev_b32_e32 v2, 3, v0
	v_ashrrev_i32_e32 v3, 31, v2
	v_ashrrev_i32_e32 v48, 6, v0
	v_lshlrev_b64 v[196:197], 1, v[2:3]
	v_add_u32_e32 v6, 0x800, v2
	v_add_u32_e32 v8, 0x1000, v2
	v_add_u32_e32 v2, 0x1800, v2
	v_lshlrev_b32_e32 v49, 4, v0
	v_and_b32_e32 v48, -2, v48
	v_ashrrev_i32_e32 v3, 31, v2
	v_and_b32_e32 v15, 31, v0
	v_lshrrev_b32_e32 v51, 3, v0
	v_lshlrev_b32_e32 v52, 1, v0
	v_lshrrev_b32_e32 v53, 1, v0
	v_and_b32_e32 v0, 0x3f0, v49
	v_and_b32_e32 v50, 0x70, v49
	v_ashrrev_i32_e32 v49, 31, v48
	v_ashrrev_i32_e32 v7, 31, v6
	v_ashrrev_i32_e32 v9, 31, v8
	v_lshlrev_b64 v[202:203], 1, v[2:3]
	v_lshlrev_b64 v[48:49], 16, v[48:49]
	v_lshl_add_u64 v[4:5], s[10:11], 0, v[196:197]
	v_lshlrev_b64 v[198:199], 1, v[6:7]
	v_lshlrev_b64 v[200:201], 1, v[8:9]
	v_lshl_add_u64 v[2:3], s[10:11], 0, v[202:203]
	s_addc_u32 s19, s11, 0
	v_lshl_add_u64 v[48:49], s[8:9], 0, v[48:49]
	v_lshl_add_u64 v[6:7], s[10:11], 0, v[198:199]
	v_lshl_add_u64 v[8:9], s[10:11], 0, v[200:201]
	global_load_dwordx4 v[16:19], v[4:5], off
	global_load_dwordx4 v[20:23], v[6:7], off
	global_load_dwordx4 v[24:27], v[8:9], off
	global_load_dwordx4 v[28:31], v[2:3], off
	v_lshl_add_u64 v[2:3], s[18:19], 0, v[196:197]
	v_lshl_add_u64 v[206:207], v[48:49], 0, v[0:1]
	global_load_dwordx4 v[32:35], v[2:3], off
	v_lshl_add_u64 v[2:3], s[18:19], 0, v[198:199]
	v_add_co_u32_e32 v48, vcc, s94, v206
	v_lshl_add_u64 v[4:5], s[18:19], 0, v[200:201]
	v_lshl_add_u64 v[6:7], s[18:19], 0, v[202:203]
	global_load_dwordx4 v[36:39], v[2:3], off
	global_load_dwordx4 v[40:43], v[4:5], off
	global_load_dwordx4 v[44:47], v[6:7], off
	v_addc_co_u32_e32 v49, vcc, 0, v207, vcc
	global_load_dwordx4 v[154:157], v[48:49], off
	global_load_dwordx4 v[158:161], v[206:207], off
	global_load_dwordx4 v[146:149], v[48:49], off offset:1024
	global_load_dwordx4 v[150:153], v[206:207], off offset:1024
	global_load_dwordx4 v[142:145], v[48:49], off offset:2048
	global_load_dwordx4 v[138:141], v[206:207], off offset:2048
	global_load_dwordx4 v[130:133], v[48:49], off offset:3072
	global_load_dwordx4 v[134:137], v[206:207], off offset:3072
	s_movk_i32 s36, 0x80
	v_and_or_b32 v15, v52, s36, v15
	v_mad_u64_u32 v[204:205], s[36:37], v51, s0, v[50:51]
	v_mov_b32_e32 v2, 0
	v_and_b32_e32 v52, 16, v53
	s_mov_b64 s[36:37], 0x10000
	s_mov_b32 s13, 0
	v_mov_b32_e32 v3, v2
	v_mov_b32_e32 v4, v2
	v_mov_b32_e32 v5, v2
	v_mov_b32_e32 v6, v2
	v_mov_b32_e32 v7, v2
	v_mov_b32_e32 v8, v2
	v_mov_b32_e32 v9, v2
	v_mov_b32_e32 v10, v2
	v_mov_b32_e32 v11, v2
	v_mov_b32_e32 v12, v2
	v_mov_b32_e32 v13, v2
	v_mov_b32_e32 v14, v2
	v_mad_u32_u24 v195, v15, s0, v52
	v_lshl_add_u64 v[208:209], v[206:207], 0, s[36:37]
	v_mov_b32_e32 v15, v2
	v_mov_b32_e32 v48, v2
	v_mov_b32_e32 v49, v2
	v_mov_b32_e32 v82, v2
	v_mov_b32_e32 v83, v2
	v_mov_b32_e32 v84, v2
	v_mov_b32_e32 v85, v2
	v_mov_b32_e32 v86, v2
	v_mov_b32_e32 v87, v2
	v_mov_b32_e32 v88, v2
	v_mov_b32_e32 v89, v2
	v_mov_b32_e32 v90, v2
	v_mov_b32_e32 v91, v2
	v_mov_b32_e32 v92, v2
	v_mov_b32_e32 v93, v2
	v_mov_b32_e32 v94, v2
	v_mov_b32_e32 v95, v2
	v_mov_b32_e32 v96, v2
	v_mov_b32_e32 v97, v2
	v_mov_b32_e32 v50, v2
	v_mov_b32_e32 v51, v2
	v_mov_b32_e32 v52, v2
	s_waitcnt vmcnt(16)
	v_add_f32_e32 v232, v212, v213
	v_add_f32_e32 v232, v232, v214
	v_add_f32_e32 v232, v232, v215
	v_add_f32_e32 v232, v232, v228
	v_add_f32_e32 v232, v232, v229
	v_add_f32_e32 v232, v232, v230
	v_add_f32_e32 v232, v232, v231
	v_add_f32_e32 v232, v232, v224
	v_add_f32_e32 v232, v232, v225
	v_add_f32_e32 v232, v232, v226
	v_add_f32_e32 v232, v232, v227
	v_add_f32_e32 v232, v232, v220
	v_add_f32_e32 v232, v232, v221
	v_add_f32_e32 v232, v232, v222
	v_add_f32_e32 v232, v232, v223
	v_fmamk_f32 v232, v232, 0x3a800000, v235
	v_cmp_gt_f32_e32 vcc, 0x800000, v232
	v_mul_f32_e32 v233, 0x4b800000, v232
	s_nop 1
	v_cndmask_b32_e32 v232, v232, v233, vcc
	v_rsq_f32_e32 v232, v232
	v_lshl_add_u32 v212, v169, 2, v244
	v_mul_f32_e32 v233, 0x45800000, v232
	v_cndmask_b32_e32 v232, v232, v233, vcc
	ds_write_b32 v212, v232
	s_waitcnt vmcnt(15)
	ds_write_b128 v204, v[16:19]
	s_waitcnt vmcnt(11)
	ds_write_b128 v204, v[32:35] offset:18432
	ds_write_b128 v204, v[20:23] offset:4608
	ds_write_b128 v204, v[24:27] offset:9216
	ds_write_b128 v204, v[28:31] offset:13824
	s_waitcnt vmcnt(10)
	ds_write_b128 v204, v[36:39] offset:23040
	s_waitcnt vmcnt(9)
	ds_write_b128 v204, v[40:43] offset:27648
	s_waitcnt vmcnt(8)
	ds_write_b128 v204, v[44:47] offset:32256
	v_mov_b32_e32 v16, v2
	v_mov_b32_e32 v17, v2
	v_mov_b32_e32 v34, v2
	v_mov_b32_e32 v35, v2
	v_mov_b32_e32 v36, v2
	v_mov_b32_e32 v37, v2
	v_mov_b32_e32 v38, v2
	v_mov_b32_e32 v39, v2
	v_mov_b32_e32 v40, v2
	v_mov_b32_e32 v41, v2
	v_mov_b32_e32 v42, v2
	v_mov_b32_e32 v43, v2
	v_mov_b32_e32 v44, v2
	v_mov_b32_e32 v45, v2
	v_mov_b32_e32 v46, v2
	v_mov_b32_e32 v47, v2
	v_mov_b32_e32 v18, v2
	v_mov_b32_e32 v19, v2
	v_mov_b32_e32 v20, v2
	v_mov_b32_e32 v21, v2
	v_mov_b32_e32 v22, v2
	v_mov_b32_e32 v23, v2
	v_mov_b32_e32 v24, v2
	v_mov_b32_e32 v25, v2
	v_mov_b32_e32 v26, v2
	v_mov_b32_e32 v27, v2
	v_mov_b32_e32 v28, v2
	v_mov_b32_e32 v29, v2
	v_mov_b32_e32 v30, v2
	v_mov_b32_e32 v31, v2
	v_mov_b32_e32 v32, v2
	v_mov_b32_e32 v33, v2
	v_mov_b32_e32 v53, v2
	v_mov_b32_e32 v54, v2
	v_mov_b32_e32 v55, v2
	v_mov_b32_e32 v56, v2
	v_mov_b32_e32 v57, v2
	v_mov_b32_e32 v58, v2
	v_mov_b32_e32 v59, v2
	v_mov_b32_e32 v60, v2
	v_mov_b32_e32 v61, v2
	v_mov_b32_e32 v62, v2
	v_mov_b32_e32 v63, v2
	v_mov_b32_e32 v64, v2
	v_mov_b32_e32 v65, v2
	v_mov_b32_e32 v98, v2
	v_mov_b32_e32 v99, v2
	v_mov_b32_e32 v100, v2
	v_mov_b32_e32 v101, v2
	v_mov_b32_e32 v102, v2
	v_mov_b32_e32 v103, v2
	v_mov_b32_e32 v104, v2
	v_mov_b32_e32 v105, v2
	v_mov_b32_e32 v106, v2
	v_mov_b32_e32 v107, v2
	v_mov_b32_e32 v108, v2
	v_mov_b32_e32 v109, v2
	v_mov_b32_e32 v110, v2
	v_mov_b32_e32 v111, v2
	v_mov_b32_e32 v112, v2
	v_mov_b32_e32 v113, v2
	v_mov_b32_e32 v66, v2
	v_mov_b32_e32 v67, v2
	v_mov_b32_e32 v68, v2
	v_mov_b32_e32 v69, v2
	v_mov_b32_e32 v70, v2
	v_mov_b32_e32 v71, v2
	v_mov_b32_e32 v72, v2
	v_mov_b32_e32 v73, v2
	v_mov_b32_e32 v74, v2
	v_mov_b32_e32 v75, v2
	v_mov_b32_e32 v76, v2
	v_mov_b32_e32 v77, v2
	v_mov_b32_e32 v78, v2
	v_mov_b32_e32 v79, v2
	v_mov_b32_e32 v80, v2
	v_mov_b32_e32 v81, v2
	v_mov_b32_e32 v114, v2
	v_mov_b32_e32 v115, v2
	v_mov_b32_e32 v116, v2
	v_mov_b32_e32 v117, v2
	v_mov_b32_e32 v118, v2
	v_mov_b32_e32 v119, v2
	v_mov_b32_e32 v120, v2
	v_mov_b32_e32 v121, v2
	v_mov_b32_e32 v122, v2
	v_mov_b32_e32 v123, v2
	v_mov_b32_e32 v124, v2
	v_mov_b32_e32 v125, v2
	v_mov_b32_e32 v126, v2
	v_mov_b32_e32 v127, v2
	v_mov_b32_e32 v128, v2
	v_mov_b32_e32 v129, v2
	s_waitcnt lgkmcnt(0)
	s_barrier

; #define A256_LOADH(kt_, hf_) { a0 = la.ld1(kt_, (hf_) * 4 + 0, tid); a1 = la.ld1(kt_, (hf_) * 4 + 1, tid); a2 = la.ld1(kt_, (hf_) * 4 + 2, tid); a3 = la.ld1(kt_, (hf_) * 4 + 3, tid); }
; template <bool swap, class LA>
; DI void gemm256_ws(const LA& la, const bf16_t* Wt, const int KS, const int nk, bf16_t* smem, f32x16 (&acc)[8]) {
;     ...
;   A256_LOADH(0, 0) A256_STH(smem, 0)
;   A256_LOADH(0, 1) A256_STH(smem, 1)
;   W256_LD(0, 0, w00, w10) W256_LD(0, 1, w01, w11) W256_LD(0, 2, w02, w12) W256_LD(0, 3, w03, w13)
;   __syncthreads();
;   const int aoff = (tbk * 128 + l32) * LDT + h * 8;
; DI void ph_in_o(const Params& P, int g, bf16_t* smem, float* s_rs) {
;     ...
;     LoadTile256 la{x2b + (size_t)(2 * mt) * 16 * 8192, 16 * 8192};
;     const bool isY = (nt >= 8 && nt < 16);
;     gemm256(la, W + (size_t)n0 * 1024, 64, 16, smem, acc, !isY);
.LBB0_194:
	s_and_b64 vcc, exec, s[18:19]
	s_cbranch_vccz .LBB0_185
	v_mov_b32_e32 v0, v234
	s_add_u32 s18, s10, 0x40000
	v_lshlrev_b32_e32 v2, 3, v0
	v_ashrrev_i32_e32 v3, 31, v2
	v_lshlrev_b64 v[196:197], 1, v[2:3]
	v_add_u32_e32 v6, 0x800, v2
	v_add_u32_e32 v8, 0x1000, v2
	v_add_u32_e32 v2, 0x1800, v2
	v_lshlrev_b32_e32 v42, 11, v0
	v_ashrrev_i32_e32 v3, 31, v2
	v_lshlrev_b32_e32 v44, 4, v0
	v_lshrrev_b32_e32 v45, 3, v0
	v_and_b32_e32 v47, 0xfffff9f, v0
	v_lshrrev_b32_e32 v46, 1, v0
	v_and_b32_e32 v50, 63, v0
	v_and_b32_e32 v0, 0x20000, v42
	v_ashrrev_i32_e32 v7, 31, v6
	v_ashrrev_i32_e32 v9, 31, v8
	v_lshlrev_b64 v[202:203], 1, v[2:3]
	v_mov_b32_e32 v43, v1
	v_and_b32_e32 v42, 0x3f0, v44
	v_and_b32_e32 v44, 0x70, v44
	v_lshl_add_u64 v[48:49], s[8:9], 0, v[0:1]
	v_lshl_add_u64 v[4:5], s[10:11], 0, v[196:197]
	v_lshlrev_b64 v[198:199], 1, v[6:7]
	v_lshlrev_b64 v[200:201], 1, v[8:9]
	v_lshl_add_u64 v[2:3], s[10:11], 0, v[202:203]
	s_addc_u32 s19, s11, 0
	v_mad_u64_u32 v[204:205], s[8:9], v45, s0, v[44:45]
	v_lshl_add_u64 v[44:45], v[0:1], 0, s[16:17]
	v_lshlrev_b32_e32 v0, 4, v50
	v_lshl_add_u64 v[42:43], v[48:49], 0, v[42:43]
	v_lshl_add_u64 v[6:7], s[10:11], 0, v[198:199]
	v_lshl_add_u64 v[8:9], s[10:11], 0, v[200:201]
	global_load_dwordx4 v[10:13], v[4:5], off
	global_load_dwordx4 v[14:17], v[6:7], off
	global_load_dwordx4 v[18:21], v[8:9], off
	global_load_dwordx4 v[22:25], v[2:3], off
	v_lshl_add_u64 v[2:3], s[18:19], 0, v[196:197]
	v_lshl_add_u64 v[208:209], v[44:45], 0, v[0:1]
	v_add_co_u32_e32 v44, vcc, s94, v42
	global_load_dwordx4 v[26:29], v[2:3], off
	v_lshl_add_u64 v[2:3], s[18:19], 0, v[198:199]
	v_addc_co_u32_e32 v45, vcc, 0, v43, vcc
	v_lshl_add_u64 v[4:5], s[18:19], 0, v[200:201]
	v_lshl_add_u64 v[6:7], s[18:19], 0, v[202:203]
	global_load_dwordx4 v[30:33], v[2:3], off
	global_load_dwordx4 v[34:37], v[4:5], off
	global_load_dwordx4 v[38:41], v[6:7], off
	global_load_dwordx4 v[154:157], v[42:43], off
	global_load_dwordx4 v[158:161], v[44:45], off
	global_load_dwordx4 v[150:153], v[42:43], off offset:1024
	global_load_dwordx4 v[146:149], v[44:45], off offset:1024
	global_load_dwordx4 v[138:141], v[42:43], off offset:2048
	global_load_dwordx4 v[142:145], v[44:45], off offset:2048
	global_load_dwordx4 v[134:137], v[42:43], off offset:3072
	global_load_dwordx4 v[130:133], v[44:45], off offset:3072
	v_mov_b32_e32 v232, v42
	v_mov_b32_e32 v233, v43
	v_mov_b32_e32 v2, 0
	v_and_b32_e32 v46, 16, v46
	v_mov_b32_e32 v219, 0x12000
	s_mov_b32 s13, 0
	v_mov_b32_e32 v3, v2
	v_mov_b32_e32 v4, v2
	v_mov_b32_e32 v5, v2
	v_mov_b32_e32 v6, v2
	v_mov_b32_e32 v7, v2
	v_mov_b32_e32 v8, v2
	v_mov_b32_e32 v9, v2
	v_mad_u64_u32 v[206:207], s[8:9], v47, s0, v[46:47]


; #define A256_LOADH(kt_, hf_) { a0 = la.ld1(kt_, (hf_) * 4 + 0, tid); a1 = la.ld1(kt_, (hf_) * 4 + 1, tid); a2 = la.ld1(kt_, (hf_) * 4 + 2, tid); a3 = la.ld1(kt_, (hf_) * 4 + 3, tid); }
; template <bool swap, class LA>
; DI void gemm256_ws(const LA& la, const bf16_t* Wt, const int KS, const int nk, bf16_t* smem, f32x16 (&acc)[8]) {
;     ...
;   A256_LOADH(0, 0) A256_STH(smem, 0)
;   A256_LOADH(0, 1) A256_STH(smem, 1)
;   W256_LD(0, 0, w00, w10) W256_LD(0, 1, w01, w11) W256_LD(0, 2, w02, w12) W256_LD(0, 3, w03, w13)
;   __syncthreads();
;   const int aoff = (tbk * 128 + l32) * LDT + h * 8;
; DI void ph_in_o(const Params& P, int g, bf16_t* smem, float* s_rs) {
;     ...
;     {
;       const float4* pp = (const float4*)(ssx + (size_t)(m0 + tid) * 16);
;       float4 a = pp[0], b = pp[1], c = pp[2], d = pp[3];
;       float s = a.x + a.y + a.z + a.w + b.x + b.y + b.z + b.w + c.x + c.y + c.z + c.w + d.x + d.y + d.z + d.w;
;       s_rs[tid] = rsqrtf(s * (1.f / 1024.f) + EPS);
	v_mov_b32_e32 v42, v2
	v_mov_b32_e32 v43, v2
	v_mov_b32_e32 v44, v2
	v_mov_b32_e32 v45, v2
	v_mov_b32_e32 v46, v2
	v_mov_b32_e32 v47, v2
	v_mov_b32_e32 v48, v2
	v_mov_b32_e32 v49, v2
	v_mov_b32_e32 v82, v2
	v_mov_b32_e32 v83, v2
	v_mov_b32_e32 v84, v2
	v_mov_b32_e32 v85, v2
	v_mov_b32_e32 v86, v2
	v_mov_b32_e32 v87, v2
	v_mov_b32_e32 v88, v2
	v_mov_b32_e32 v89, v2
	v_mov_b32_e32 v90, v2
	v_mov_b32_e32 v91, v2
	v_mov_b32_e32 v92, v2
	v_mov_b32_e32 v93, v2
	v_mov_b32_e32 v94, v2
	v_mov_b32_e32 v95, v2
	s_waitcnt vmcnt(16)
	v_add_f32_e32 v216, v212, v213
	v_add_f32_e32 v216, v216, v214
	v_add_f32_e32 v216, v216, v215
	v_add_f32_e32 v216, v216, v228
	v_add_f32_e32 v216, v216, v229
	v_add_f32_e32 v216, v216, v230
	v_add_f32_e32 v216, v216, v231
	v_add_f32_e32 v216, v216, v224
	v_add_f32_e32 v216, v216, v225
	v_add_f32_e32 v216, v216, v226
	v_add_f32_e32 v216, v216, v227
	v_add_f32_e32 v216, v216, v220
	v_add_f32_e32 v216, v216, v221
	v_add_f32_e32 v216, v216, v222
	v_add_f32_e32 v216, v216, v223
	v_fmamk_f32 v216, v216, 0x3a800000, v235
	v_cmp_gt_f32_e32 vcc, 0x800000, v216
	v_mul_f32_e32 v217, 0x4b800000, v216
	s_nop 1
	v_cndmask_b32_e32 v216, v216, v217, vcc
	v_rsq_f32_e32 v216, v216
	v_lshl_add_u32 v212, v169, 2, v244
	v_mul_f32_e32 v217, 0x45800000, v216
	v_cndmask_b32_e32 v216, v216, v217, vcc
	ds_write_b32 v212, v216
	s_waitcnt vmcnt(15)
	ds_write_b128 v204, v[10:13]
	s_waitcnt vmcnt(11)
	ds_write_b128 v204, v[26:29] offset:18432
	ds_write_b128 v204, v[14:17] offset:4608
	ds_write_b128 v204, v[18:21] offset:9216
	ds_write_b128 v204, v[22:25] offset:13824
	s_waitcnt vmcnt(10)
	ds_write_b128 v204, v[30:33] offset:23040
	s_waitcnt vmcnt(9)
	ds_write_b128 v204, v[34:37] offset:27648
	s_waitcnt vmcnt(8)
	ds_write_b128 v204, v[38:41] offset:32256
	v_mov_b32_e32 v10, v2
	v_mov_b32_e32 v11, v2
	v_mov_b32_e32 v12, v2
	v_mov_b32_e32 v13, v2
	v_mov_b32_e32 v14, v2
	v_mov_b32_e32 v15, v2
	v_mov_b32_e32 v16, v2
	v_mov_b32_e32 v17, v2
	v_mov_b32_e32 v34, v2
	v_mov_b32_e32 v35, v2
	v_mov_b32_e32 v36, v2
	v_mov_b32_e32 v37, v2
	v_mov_b32_e32 v38, v2
	v_mov_b32_e32 v39, v2
	v_mov_b32_e32 v40, v2
	v_mov_b32_e32 v41, v2
	v_mov_b32_e32 v18, v2
	v_mov_b32_e32 v19, v2
	v_mov_b32_e32 v20, v2
	v_mov_b32_e32 v21, v2
	v_mov_b32_e32 v22, v2
	v_mov_b32_e32 v23, v2
	v_mov_b32_e32 v24, v2
	v_mov_b32_e32 v25, v2
	v_mov_b32_e32 v26, v2
	v_mov_b32_e32 v27, v2
	v_mov_b32_e32 v28, v2
	v_mov_b32_e32 v29, v2
	v_mov_b32_e32 v30, v2
	v_mov_b32_e32 v31, v2
	v_mov_b32_e32 v32, v2
	v_mov_b32_e32 v33, v2
	v_mov_b32_e32 v96, v2
	v_mov_b32_e32 v97, v2
	v_mov_b32_e32 v50, v2
	v_mov_b32_e32 v51, v2
	v_mov_b32_e32 v52, v2
	v_mov_b32_e32 v53, v2
	v_mov_b32_e32 v54, v2
	v_mov_b32_e32 v55, v2
	v_mov_b32_e32 v56, v2
	v_mov_b32_e32 v57, v2
	v_mov_b32_e32 v58, v2
	v_mov_b32_e32 v59, v2
	v_mov_b32_e32 v60, v2
	v_mov_b32_e32 v61, v2
	v_mov_b32_e32 v62, v2
	v_mov_b32_e32 v63, v2
	v_mov_b32_e32 v64, v2
	v_mov_b32_e32 v65, v2
	v_mov_b32_e32 v98, v2
	v_mov_b32_e32 v99, v2
	v_mov_b32_e32 v100, v2
	v_mov_b32_e32 v101, v2
	v_mov_b32_e32 v102, v2
	v_mov_b32_e32 v103, v2
	v_mov_b32_e32 v104, v2
	v_mov_b32_e32 v105, v2
	v_mov_b32_e32 v106, v2
	v_mov_b32_e32 v107, v2
	v_mov_b32_e32 v108, v2
	v_mov_b32_e32 v109, v2
	v_mov_b32_e32 v110, v2
	v_mov_b32_e32 v111, v2
	v_mov_b32_e32 v112, v2
	v_mov_b32_e32 v113, v2
	v_mov_b32_e32 v66, v2
	v_mov_b32_e32 v67, v2
	v_mov_b32_e32 v68, v2
	v_mov_b32_e32 v69, v2
	v_mov_b32_e32 v70, v2
	v_mov_b32_e32 v71, v2
	v_mov_b32_e32 v72, v2
	v_mov_b32_e32 v73, v2
	v_mov_b32_e32 v74, v2
	v_mov_b32_e32 v75, v2
	v_mov_b32_e32 v76, v2
	v_mov_b32_e32 v77, v2
	v_mov_b32_e32 v78, v2
	v_mov_b32_e32 v79, v2
	v_mov_b32_e32 v80, v2
	v_mov_b32_e32 v81, v2
	v_mov_b32_e32 v114, v2
	v_mov_b32_e32 v115, v2
	v_mov_b32_e32 v116, v2
	v_mov_b32_e32 v117, v2
	v_mov_b32_e32 v118, v2
	v_mov_b32_e32 v119, v2
	v_mov_b32_e32 v120, v2
	v_mov_b32_e32 v121, v2
	v_mov_b32_e32 v122, v2
	v_mov_b32_e32 v123, v2
	v_mov_b32_e32 v124, v2
	v_mov_b32_e32 v125, v2
	v_mov_b32_e32 v126, v2
	v_mov_b32_e32 v127, v2
	v_mov_b32_e32 v128, v2
	v_mov_b32_e32 v129, v2
	s_waitcnt lgkmcnt(0)
	s_barrier
